# v20: GLA pass B output epilogue: the four per-token-group partial-sum reads issued together and the four sqrt/divide (rstd) chains computed interleaved up front; per-group code consumes the precompute
# baseline (speedup 1.0000x reference)
; #define LAS __attribute__((address_space(3)))
; template <bool FULL>
; __device__ __forceinline__ void gla_pass(const Params& P, LAS unsigned char* lds, f32x4 (&S)[8][2], int bh, int c0, int L, bool dry) {
;     ...
; #pragma unroll
;             for (int tt = 0; tt < 4; ++tt) {
;                 const int t = 16 * tt + fr;
;                 const f32x4 r0 = *(const LAS f32x4*)(red + t * 8), r1 = *(const LAS f32x4*)(red + t * 8 + 4);
;                 const float rstd = 1.0f / sqrtf(((r0[0] + r0[1]) + (r0[2] + r0[3]) + (r1[0] + r1[1]) + (r1[2] + r1[3])) * (1.0f / 256.0f) + RMS_EPS);
.LBB0_698:
	v_mov_b32_e32 v140, v238
	v_mov_b32_e32 v141, v239
	v_mov_b32_e32 v142, v240
	v_mov_b32_e32 v143, v241
	v_mov_b32_e32 v136, v242
	v_mov_b32_e32 v137, v243
	v_mov_b32_e32 v138, v244
	v_mov_b32_e32 v139, v245
	ds_read_b128 v[208:211], v190
	ds_read_b128 v[212:215], v190 offset:16
	ds_read_b128 v[216:219], v205
	ds_read_b128 v[232:235], v205 offset:16
	ds_read_b128 v[252:255], v206
	ds_read_b128 v[246:249], v206 offset:16
	ds_read_b64 v[220:221], v207
	ds_read_b64 v[230:231], v207 offset:8
	ds_read_b64 v[250:251], v207 offset:16
	ds_read_b64 v[166:167], v207 offset:24
	s_waitcnt lgkmcnt(0)
	v_add_f32_e32 v208, v209, v208
	v_add_f32_e32 v216, v217, v216
	v_add_f32_e32 v252, v253, v252
	v_add_f32_e32 v220, v221, v220
	v_add_f32_e32 v210, v210, v211
	v_add_f32_e32 v218, v218, v219
	v_add_f32_e32 v254, v254, v255
	v_add_f32_e32 v230, v230, v231
	v_add_f32_e32 v214, v214, v215
	v_add_f32_e32 v234, v234, v235
	v_add_f32_e32 v248, v248, v249
	v_add_f32_e32 v166, v166, v167
	v_add_f32_e32 v212, v212, v213
	v_add_f32_e32 v232, v232, v233
	v_add_f32_e32 v246, v246, v247
	v_add_f32_e32 v250, v250, v251
	v_add_f32_e32 v208, v208, v210
	v_add_f32_e32 v216, v216, v218
	v_add_f32_e32 v252, v252, v254
	v_add_f32_e32 v220, v220, v230
	v_add_f32_e32 v208, v208, v212
	v_add_f32_e32 v216, v216, v232
	v_add_f32_e32 v252, v252, v246
	v_add_f32_e32 v220, v220, v250
	v_add_f32_e32 v208, v214, v208
	v_add_f32_e32 v216, v234, v216
	v_add_f32_e32 v252, v248, v252
	v_add_f32_e32 v220, v166, v220
	v_fmamk_f32 v208, v208, 0x3b800000, v202
	v_fmamk_f32 v216, v216, 0x3b800000, v202
	v_fmamk_f32 v252, v252, 0x3b800000, v202
	v_fmamk_f32 v220, v220, 0x3b800000, v202
	v_mul_f32_e32 v209, 0x4f800000, v208
	v_mul_f32_e32 v217, 0x4f800000, v216
	v_mul_f32_e32 v253, 0x4f800000, v252
	v_mul_f32_e32 v221, 0x4f800000, v220
	v_cmp_gt_f32_e64 s[46:47], s26, v208
	v_cmp_gt_f32_e64 s[48:49], s26, v216
	v_cmp_gt_f32_e64 s[50:51], s26, v252
	v_cmp_gt_f32_e64 s[52:53], s26, v220
	v_cndmask_b32_e64 v208, v208, v209, s[46:47]
	v_cndmask_b32_e64 v216, v216, v217, s[48:49]
	v_cndmask_b32_e64 v252, v252, v253, s[50:51]
	v_cndmask_b32_e64 v220, v220, v221, s[52:53]
	v_sqrt_f32_e32 v209, v208
	v_sqrt_f32_e32 v217, v216
	v_sqrt_f32_e32 v253, v252
	v_sqrt_f32_e32 v221, v220
	v_add_u32_e32 v210, -1, v209
	v_add_u32_e32 v218, -1, v217
	v_add_u32_e32 v254, -1, v253
	v_add_u32_e32 v230, -1, v221
	v_add_u32_e32 v211, 1, v209
	v_add_u32_e32 v219, 1, v217
	v_add_u32_e32 v255, 1, v253
	v_add_u32_e32 v231, 1, v221
	v_fma_f32 v212, -v210, v209, v208
	v_fma_f32 v232, -v218, v217, v216
	v_fma_f32 v246, -v254, v253, v252
	v_fma_f32 v250, -v230, v221, v220
	v_fma_f32 v213, -v211, v209, v208
	v_fma_f32 v233, -v219, v217, v216
	v_fma_f32 v247, -v255, v253, v252
	v_fma_f32 v251, -v231, v221, v220
	v_cmp_ge_f32_e64 s[54:55], 0, v212
	v_cmp_ge_f32_e64 s[56:57], 0, v232
	v_cmp_ge_f32_e64 s[58:59], 0, v246
	v_cmp_ge_f32_e64 s[60:61], 0, v250
	v_cndmask_b32_e64 v209, v209, v210, s[54:55]
	v_cndmask_b32_e64 v217, v217, v218, s[56:57]
	v_cndmask_b32_e64 v253, v253, v254, s[58:59]
	v_cndmask_b32_e64 v221, v221, v230, s[60:61]
	v_cmp_lt_f32_e64 s[54:55], 0, v213
	v_cmp_lt_f32_e64 s[56:57], 0, v233
	v_cmp_lt_f32_e64 s[58:59], 0, v247
	v_cmp_lt_f32_e64 s[60:61], 0, v251
	v_cndmask_b32_e64 v209, v209, v211, s[54:55]
	v_cndmask_b32_e64 v217, v217, v219, s[56:57]
	v_cndmask_b32_e64 v253, v253, v255, s[58:59]
	v_cndmask_b32_e64 v221, v221, v231, s[60:61]
	v_mul_f32_e32 v210, 0x37800000, v209
	v_mul_f32_e32 v218, 0x37800000, v217
	v_mul_f32_e32 v254, 0x37800000, v253
	v_mul_f32_e32 v230, 0x37800000, v221
	v_cndmask_b32_e64 v209, v209, v210, s[46:47]
	v_cndmask_b32_e64 v217, v217, v218, s[48:49]
	v_cndmask_b32_e64 v253, v253, v254, s[50:51]
	v_cndmask_b32_e64 v221, v221, v230, s[52:53]
	v_cmp_class_f32_e64 s[54:55], v208, v203
	v_cmp_class_f32_e64 s[56:57], v216, v203
	v_cmp_class_f32_e64 s[58:59], v252, v203
	v_cmp_class_f32_e64 s[60:61], v220, v203
	v_cndmask_b32_e64 v208, v209, v208, s[54:55]
	v_cndmask_b32_e64 v216, v217, v216, s[56:57]
	v_cndmask_b32_e64 v252, v253, v252, s[58:59]
	v_cndmask_b32_e64 v220, v221, v220, s[60:61]
	v_div_scale_f32 v209, s[54:55], v208, v208, 1.0
	v_div_scale_f32 v217, s[56:57], v216, v216, 1.0
	v_div_scale_f32 v253, s[58:59], v252, v252, 1.0
	v_div_scale_f32 v221, s[60:61], v220, v220, 1.0
	v_rcp_f32_e32 v210, v209
	v_rcp_f32_e32 v218, v217
	v_rcp_f32_e32 v254, v253
	v_rcp_f32_e32 v230, v221
	v_fma_f32 v212, -v209, v210, 1.0
	v_fma_f32 v232, -v217, v218, 1.0
	v_fma_f32 v246, -v253, v254, 1.0
	v_fma_f32 v250, -v221, v230, 1.0
	v_fmac_f32_e32 v210, v212, v210
	v_fmac_f32_e32 v218, v232, v218
	v_fmac_f32_e32 v254, v246, v254
	v_fmac_f32_e32 v230, v250, v230
	v_div_scale_f32 v211, vcc, 1.0, v208, 1.0
	v_mul_f32_e32 v212, v211, v210
	v_fma_f32 v213, -v209, v212, v211
	v_fmac_f32_e32 v212, v213, v210
	v_fma_f32 v209, -v209, v212, v211
	v_div_fmas_f32 v209, v209, v210, v212
	v_div_fixup_f32 v222, v209, v208, 1.0
	v_div_scale_f32 v219, vcc, 1.0, v216, 1.0
	v_mul_f32_e32 v232, v219, v218
	v_fma_f32 v233, -v217, v232, v219
	v_fmac_f32_e32 v232, v233, v218
	v_fma_f32 v217, -v217, v232, v219
	v_div_fmas_f32 v217, v217, v218, v232
	v_div_fixup_f32 v224, v217, v216, 1.0
	v_div_scale_f32 v255, vcc, 1.0, v252, 1.0
	v_mul_f32_e32 v246, v255, v254
	v_fma_f32 v247, -v253, v246, v255
	v_fmac_f32_e32 v246, v247, v254
	v_fma_f32 v253, -v253, v246, v255
	v_div_fmas_f32 v253, v253, v254, v246
	v_div_fixup_f32 v226, v253, v252, 1.0
	v_div_scale_f32 v231, vcc, 1.0, v220, 1.0
	v_mul_f32_e32 v250, v231, v230
	v_fma_f32 v251, -v221, v250, v231
	v_fmac_f32_e32 v250, v251, v230
	v_fma_f32 v221, -v221, v250, v231
	v_div_fmas_f32 v221, v221, v230, v250
	v_div_fixup_f32 v228, v221, v220, 1.0
	s_waitcnt vmcnt(7)
; #define LAS __attribute__((address_space(3)))
; __device__ __forceinline__ float bflo(unsigned w) { return __uint_as_float(w << 16); }
; __device__ __forceinline__ float bfhi(unsigned w) { return __uint_as_float(w & 0xffff0000u); }
; __device__ __forceinline__ unsigned pk2(float lo, float hi) { return f2bf(lo) | (f2bf(hi) << 16); }
; template <bool FULL>
; __device__ __forceinline__ void gla_pass(const Params& P, LAS unsigned char* lds, f32x4 (&S)[8][2], int bh, int c0, int L, bool dry) {
;     ...
; #pragma unroll
;             for (int tt = 0; tt < 4; ++tt) {
;                 const int t = 16 * tt + fr;
;                 const f32x4 r0 = *(const LAS f32x4*)(red + t * 8), r1 = *(const LAS f32x4*)(red + t * 8 + 4);
;                 const float rstd = 1.0f / sqrtf(((r0[0] + r0[1]) + (r0[2] + r0[3]) + (r1[0] + r1[1]) + (r1[2] + r1[3])) * (1.0f / 256.0f) + RMS_EPS);
; #pragma unroll
;                 for (int vt = 0; vt < 2; ++vt) {
;                     bf16_t* op = (bf16_t*)P.out + (row0 + t) * 2048 + 1024 + h * 256 + 32 * w + 16 * vt + 4 * g;
;                     const u32x2 z = zb[vt][tt]; const f32x4 ov = o[vt][tt] * rstd * gn[vt];
;                     u32x2 r; r.x = pk2(ov[0] * bflo(z.x), ov[1] * bfhi(z.x)); r.y = pk2(ov[2] * bflo(z.y), ov[3] * bfhi(z.y));
;                     if (!dry) *(u32x2*)op = r;
;                 }
	v_lshlrev_b32_e32 v217, 16, v181
	v_lshlrev_b32_e32 v216, 16, v180
	v_and_b32_e32 v181, 0xffff0000, v181
	s_waitcnt lgkmcnt(1)
	s_waitcnt lgkmcnt(0)
	v_and_b32_e32 v180, 0xffff0000, v180
	s_waitcnt vmcnt(4)
	v_lshlrev_b32_e32 v219, 16, v179
	v_lshlrev_b32_e32 v218, 16, v178
	v_and_b32_e32 v179, 0xffff0000, v179
	v_and_b32_e32 v178, 0xffff0000, v178
	v_add_u32_e32 v160, s27, v193
	v_lshlrev_b64 v[208:209], 12, v[160:161]
	v_lshl_add_u64 v[208:209], v[168:169], 0, v[208:209]
	s_add_i32 s27, s27, 64
	s_add_i32 s0, s0, 1
	v_lshl_add_u64 v[170:171], v[170:171], 0, s[14:15]
	s_cmpk_eq_i32 s27, 0x400
	v_pk_mul_f32 v[134:135], v[134:135], v[222:223] op_sel_hi:[1,0]
	v_pk_mul_f32 v[132:133], v[132:133], v[222:223] op_sel_hi:[1,0]
	v_pk_mul_f32 v[130:131], v[130:131], v[222:223] op_sel_hi:[1,0]
	v_pk_mul_f32 v[128:129], v[128:129], v[222:223] op_sel_hi:[1,0]
	v_lshl_add_u64 v[172:173], v[172:173], 0, s[16:17]
	s_waitcnt vmcnt(0)
	v_pk_mul_f32 v[132:133], v[140:141], v[132:133]
	v_pk_mul_f32 v[134:135], v[142:143], v[134:135]
	v_pk_mul_f32 v[128:129], v[136:137], v[128:129]
	v_pk_mul_f32 v[130:131], v[138:139], v[130:131]
	v_mov_b32_e32 v210, v132
	v_mov_b32_e32 v211, v134
	v_mov_b32_e32 v134, v133
	v_mov_b32_e32 v132, v128
	v_mov_b32_e32 v133, v130
	v_mov_b32_e32 v130, v129
	v_pk_mul_f32 v[128:129], v[210:211], v[216:217]
	v_pk_mul_f32 v[134:135], v[134:135], v[180:181]
	v_pk_mul_f32 v[178:179], v[130:131], v[178:179]
	v_cvt_pk_bf16_f32 v254, v128, v134
	v_cvt_pk_bf16_f32 v253, v129, v135
	v_pk_mul_f32 v[132:133], v[132:133], v[218:219]
	v_mov_b32_e32 v129, v253
	v_mov_b32_e32 v128, v254
	global_store_dwordx2 v[208:209], v[128:129], off offset:2048
	v_cvt_pk_bf16_f32 v232, v132, v178
	v_cvt_pk_bf16_f32 v255, v133, v179
	s_waitcnt lgkmcnt(1)
	s_waitcnt lgkmcnt(0)
	s_nop 1
	s_nop 0
	s_nop 0
	s_nop 1
	s_nop 1
	v_mov_b32_e32 v129, v255
	v_mov_b32_e32 v128, v232
	global_store_dwordx2 v[208:209], v[128:129], off offset:2080
	v_pk_mul_f32 v[126:127], v[126:127], v[224:225] op_sel_hi:[1,0]
	v_pk_mul_f32 v[124:125], v[124:125], v[224:225] op_sel_hi:[1,0]
	v_pk_mul_f32 v[126:127], v[142:143], v[126:127]
	v_pk_mul_f32 v[124:125], v[140:141], v[124:125]
	v_lshlrev_b32_e32 v133, 16, v177
	v_lshlrev_b32_e32 v132, 16, v176
	v_mov_b32_e32 v134, v124
	v_mov_b32_e32 v135, v126
	v_pk_mul_f32 v[132:133], v[134:135], v[132:133]
	v_and_b32_e32 v135, 0xffff0000, v177
	v_and_b32_e32 v134, 0xffff0000, v176
	v_mov_b32_e32 v126, v125
	v_pk_mul_f32 v[124:125], v[126:127], v[134:135]
	s_nop 0
	v_and_b32_sdwa v129, v125, v204 dst_sel:DWORD dst_unused:UNUSED_PAD src0_sel:WORD_1 src1_sel:DWORD
	v_cvt_pk_bf16_f32 v234, v132, v124
	v_add_u32_e32 v130, 16, v160
	v_mov_b32_e32 v131, v161
	v_cvt_pk_bf16_f32 v233, v133, v125
	v_lshlrev_b64 v[130:131], 12, v[130:131]
	v_pk_mul_f32 v[122:123], v[122:123], v[224:225] op_sel_hi:[1,0]
	v_pk_mul_f32 v[120:121], v[120:121], v[224:225] op_sel_hi:[1,0]
	v_mov_b32_e32 v125, v233
	v_mov_b32_e32 v124, v234
	v_lshl_add_u64 v[130:131], v[168:169], 0, v[130:131]
	v_pk_mul_f32 v[120:121], v[136:137], v[120:121]
	v_pk_mul_f32 v[122:123], v[138:139], v[122:123]
	global_store_dwordx2 v[130:131], v[124:125], off offset:2048
	v_lshlrev_b32_e32 v125, 16, v175
	v_lshlrev_b32_e32 v124, 16, v174
	v_mov_b32_e32 v126, v120
	v_mov_b32_e32 v127, v122
	v_pk_mul_f32 v[124:125], v[126:127], v[124:125]
	v_and_b32_e32 v127, 0xffff0000, v175
	v_and_b32_e32 v126, 0xffff0000, v174
	v_mov_b32_e32 v122, v121
	v_pk_mul_f32 v[128:129], v[122:123], v[126:127]
	s_nop 0
	v_cvt_pk_bf16_f32 v237, v124, v128
	v_cvt_pk_bf16_f32 v235, v125, v129
	s_waitcnt lgkmcnt(1)
	s_waitcnt lgkmcnt(0)
; #define LAS __attribute__((address_space(3)))
; __device__ __forceinline__ float bflo(unsigned w) { return __uint_as_float(w << 16); }
; __device__ __forceinline__ float bfhi(unsigned w) { return __uint_as_float(w & 0xffff0000u); }
; __device__ __forceinline__ unsigned pk2(float lo, float hi) { return f2bf(lo) | (f2bf(hi) << 16); }
; template <bool FULL>
; __device__ __forceinline__ void gla_pass(const Params& P, LAS unsigned char* lds, f32x4 (&S)[8][2], int bh, int c0, int L, bool dry) {
;     ...
; #pragma unroll
;             for (int tt = 0; tt < 4; ++tt) {
;                 const int t = 16 * tt + fr;
;                 const f32x4 r0 = *(const LAS f32x4*)(red + t * 8), r1 = *(const LAS f32x4*)(red + t * 8 + 4);
;                 const float rstd = 1.0f / sqrtf(((r0[0] + r0[1]) + (r0[2] + r0[3]) + (r1[0] + r1[1]) + (r1[2] + r1[3])) * (1.0f / 256.0f) + RMS_EPS);
; #pragma unroll
;                 for (int vt = 0; vt < 2; ++vt) {
;                     bf16_t* op = (bf16_t*)P.out + (row0 + t) * 2048 + 1024 + h * 256 + 32 * w + 16 * vt + 4 * g;
;                     const u32x2 z = zb[vt][tt]; const f32x4 ov = o[vt][tt] * rstd * gn[vt];
;                     u32x2 r; r.x = pk2(ov[0] * bflo(z.x), ov[1] * bfhi(z.x)); r.y = pk2(ov[2] * bflo(z.y), ov[3] * bfhi(z.y));
;                     if (!dry) *(u32x2*)op = r;
;                 }
;             }
;         }
	s_nop 1
	s_nop 0
	s_nop 0
	s_nop 1
	s_nop 1
	v_mov_b32_e32 v121, v235
	v_mov_b32_e32 v120, v237
	global_store_dwordx2 v[130:131], v[120:121], off offset:2080
	v_pk_mul_f32 v[110:111], v[110:111], v[226:227] op_sel_hi:[1,0]
	v_pk_mul_f32 v[108:109], v[108:109], v[226:227] op_sel_hi:[1,0]
	v_pk_mul_f32 v[110:111], v[142:143], v[110:111]
	v_pk_mul_f32 v[108:109], v[140:141], v[108:109]
	v_lshlrev_b32_e32 v125, 16, v151
	v_lshlrev_b32_e32 v124, 16, v150
	v_mov_b32_e32 v126, v108
	v_mov_b32_e32 v127, v110
	v_pk_mul_f32 v[124:125], v[126:127], v[124:125]
	v_and_b32_e32 v127, 0xffff0000, v151
	v_and_b32_e32 v126, 0xffff0000, v150
	v_mov_b32_e32 v110, v109
	v_pk_mul_f32 v[108:109], v[110:111], v[126:127]
	s_nop 0
	v_and_b32_sdwa v121, v109, v204 dst_sel:DWORD dst_unused:UNUSED_PAD src0_sel:WORD_1 src1_sel:DWORD
	v_cvt_pk_bf16_f32 v253, v124, v108
	v_add_u32_e32 v122, 32, v160
	v_mov_b32_e32 v123, v161
	v_cvt_pk_bf16_f32 v252, v125, v109
	v_lshlrev_b64 v[122:123], 12, v[122:123]
	v_pk_mul_f32 v[106:107], v[106:107], v[226:227] op_sel_hi:[1,0]
	v_pk_mul_f32 v[104:105], v[104:105], v[226:227] op_sel_hi:[1,0]
	v_mov_b32_e32 v109, v252
	v_mov_b32_e32 v108, v253
	v_lshl_add_u64 v[122:123], v[168:169], 0, v[122:123]
	v_pk_mul_f32 v[104:105], v[136:137], v[104:105]
	v_pk_mul_f32 v[106:107], v[138:139], v[106:107]
	global_store_dwordx2 v[122:123], v[108:109], off offset:2048
	v_lshlrev_b32_e32 v109, 16, v149
	v_lshlrev_b32_e32 v108, 16, v148
	v_mov_b32_e32 v110, v104
	v_mov_b32_e32 v111, v106
	v_pk_mul_f32 v[108:109], v[110:111], v[108:109]
	v_and_b32_e32 v111, 0xffff0000, v149
	v_and_b32_e32 v110, 0xffff0000, v148
	v_mov_b32_e32 v106, v105
	v_pk_mul_f32 v[120:121], v[106:107], v[110:111]
	s_nop 0
	v_cvt_pk_bf16_f32 v255, v108, v120
	v_cvt_pk_bf16_f32 v254, v109, v121
	s_waitcnt lgkmcnt(1)
	s_waitcnt lgkmcnt(0)
	s_nop 1
	v_add_u32_e32 v160, 48, v160
	s_nop 0
	s_nop 1
	s_nop 1
	v_mov_b32_e32 v105, v254
	v_mov_b32_e32 v104, v255
	global_store_dwordx2 v[122:123], v[104:105], off offset:2080
	v_pk_mul_f32 v[108:109], v[118:119], v[228:229] op_sel_hi:[1,0]
	v_pk_mul_f32 v[110:111], v[116:117], v[228:229] op_sel_hi:[1,0]
	v_pk_mul_f32 v[108:109], v[142:143], v[108:109]
	v_pk_mul_f32 v[110:111], v[140:141], v[110:111]
	v_lshlrev_b32_e32 v117, 16, v147
	v_lshlrev_b32_e32 v116, 16, v146
	v_mov_b32_e32 v118, v110
	v_mov_b32_e32 v119, v108
	v_pk_mul_f32 v[116:117], v[118:119], v[116:117]
	v_and_b32_e32 v119, 0xffff0000, v147
	v_and_b32_e32 v118, 0xffff0000, v146
	v_mov_b32_e32 v108, v111
	v_pk_mul_f32 v[108:109], v[108:109], v[118:119]
	s_nop 0
	v_cvt_pk_bf16_f32 v233, v116, v108
	v_and_b32_sdwa v105, v117, v204 dst_sel:DWORD dst_unused:UNUSED_PAD src0_sel:WORD_1 src1_sel:DWORD
	v_cvt_pk_bf16_f32 v232, v117, v109
	v_lshlrev_b64 v[106:107], 12, v[160:161]
	v_add3_u32 v105, v117, v105, s1
	v_mov_b32_e32 v109, v232
	v_mov_b32_e32 v108, v233
	v_lshl_add_u64 v[106:107], v[168:169], 0, v[106:107]
	global_store_dwordx2 v[106:107], v[108:109], off offset:2048
	v_pk_mul_f32 v[108:109], v[114:115], v[228:229] op_sel_hi:[1,0]
	v_pk_mul_f32 v[104:105], v[112:113], v[228:229] op_sel_hi:[1,0]
	v_pk_mul_f32 v[108:109], v[138:139], v[108:109]
	v_pk_mul_f32 v[104:105], v[136:137], v[104:105]
	v_lshlrev_b32_e32 v111, 16, v145
	v_lshlrev_b32_e32 v110, 16, v144
	v_mov_b32_e32 v112, v104
	v_mov_b32_e32 v113, v108
	v_pk_mul_f32 v[110:111], v[112:113], v[110:111]
	v_and_b32_e32 v113, 0xffff0000, v145
	v_and_b32_e32 v112, 0xffff0000, v144
	v_mov_b32_e32 v108, v105
	v_pk_mul_f32 v[104:105], v[108:109], v[112:113]
	s_nop 0
	v_cvt_pk_bf16_f32 v235, v110, v104
	v_cvt_pk_bf16_f32 v234, v111, v105
	v_mov_b32_e32 v105, v234
	v_mov_b32_e32 v104, v235
	global_store_dwordx2 v[106:107], v[104:105], off offset:2080
	s_barrier
	s_cbranch_scc1 .LBB0_714
